# HGRN gate prologue regenerated: per value 4 transcendentals (exp, log, rcp, log) instead of 6, using E=exp(min(-x,60)): logsigmoid=min(x,-ln(1+E)), 1-sigmoid=E/(1+E); all f32
# speedup vs baseline: 1.0074x; 1.0074x over previous
.LBB0_234:
	v_sub_f32_e32 v204, 1.0, v36
	v_lshlrev_b32_e32 v40, 16, v40
	v_lshlrev_b32_e32 v51, 16, v51
	v_lshlrev_b32_e32 v50, 16, v50
	v_lshlrev_b32_e32 v49, 16, v49
	v_max_f32_e64 v186, -v40, -v40
	v_max_f32_e64 v190, -v51, -v51
	v_max_f32_e64 v194, -v50, -v50
	v_max_f32_e64 v198, -v49, -v49
	v_min_f32_e32 v186, 0x42700000, v186
	v_min_f32_e32 v190, 0x42700000, v190
	v_min_f32_e32 v194, 0x42700000, v194
	v_min_f32_e32 v198, 0x42700000, v198
	v_mul_f32_e32 v186, 0x3fb8aa3b, v186
	v_mul_f32_e32 v190, 0x3fb8aa3b, v190
	v_mul_f32_e32 v194, 0x3fb8aa3b, v194
	v_mul_f32_e32 v198, 0x3fb8aa3b, v198
	v_exp_f32_e32 v186, v186
	v_exp_f32_e32 v190, v190
	v_exp_f32_e32 v194, v194
	v_exp_f32_e32 v198, v198
	v_add_f32_e32 v187, 1.0, v186
	v_add_f32_e32 v191, 1.0, v190
	v_add_f32_e32 v195, 1.0, v194
	v_add_f32_e32 v199, 1.0, v198
	v_fma_f32 v189, v186, v36, 1.0
	v_fma_f32 v193, v190, v36, 1.0
	v_fma_f32 v197, v194, v36, 1.0
	v_fma_f32 v201, v198, v36, 1.0
	v_rcp_f32_e32 v188, v187
	v_rcp_f32_e32 v192, v191
	v_rcp_f32_e32 v196, v195
	v_rcp_f32_e32 v200, v199
	v_log_f32_e32 v187, v187
	v_log_f32_e32 v191, v191
	v_log_f32_e32 v195, v195
	v_log_f32_e32 v199, v199
	v_log_f32_e32 v189, v189
	v_log_f32_e32 v193, v193
	v_log_f32_e32 v197, v197
	v_log_f32_e32 v201, v201
	v_mul_f32_e32 v188, v186, v188
	v_mul_f32_e32 v192, v190, v192
	v_mul_f32_e32 v196, v194, v196
	v_mul_f32_e32 v200, v198, v200
	v_mul_f32_e32 v187, 0xbf317218, v187
	v_mul_f32_e32 v191, 0xbf317218, v191
	v_mul_f32_e32 v195, 0xbf317218, v195
	v_mul_f32_e32 v199, 0xbf317218, v199
	v_mul_f32_e32 v144, v188, v204
	v_mul_f32_e32 v145, v192, v204
	v_mul_f32_e32 v146, v196, v204
	v_mul_f32_e32 v147, v200, v204
	v_min_f32_e32 v187, v40, v187
	v_min_f32_e32 v191, v51, v191
	v_min_f32_e32 v195, v50, v195
	v_min_f32_e32 v199, v49, v199
	v_fmac_f32_e32 v187, 0x3f317218, v189
	v_fmac_f32_e32 v191, 0x3f317218, v193
	v_fmac_f32_e32 v195, 0x3f317218, v197
	v_fmac_f32_e32 v199, 0x3f317218, v201
	v_add_f32_e32 v128, 0, v187
	v_add_f32_e32 v129, v191, v128
	v_add_f32_e32 v130, v195, v129
	v_add_f32_e32 v131, v199, v130
	v_lshlrev_b32_e32 v48, 16, v48
	v_lshlrev_b32_e32 v47, 16, v47
	v_lshlrev_b32_e32 v46, 16, v46
	v_lshlrev_b32_e32 v45, 16, v45
	v_max_f32_e64 v186, -v48, -v48
	v_max_f32_e64 v190, -v47, -v47
	v_max_f32_e64 v194, -v46, -v46
	v_max_f32_e64 v198, -v45, -v45
	v_min_f32_e32 v186, 0x42700000, v186
	v_min_f32_e32 v190, 0x42700000, v190
	v_min_f32_e32 v194, 0x42700000, v194
	v_min_f32_e32 v198, 0x42700000, v198
	v_mul_f32_e32 v186, 0x3fb8aa3b, v186
	v_mul_f32_e32 v190, 0x3fb8aa3b, v190
	v_mul_f32_e32 v194, 0x3fb8aa3b, v194
	v_mul_f32_e32 v198, 0x3fb8aa3b, v198
	v_exp_f32_e32 v186, v186
	v_exp_f32_e32 v190, v190
	v_exp_f32_e32 v194, v194
	v_exp_f32_e32 v198, v198
	v_add_f32_e32 v187, 1.0, v186
	v_add_f32_e32 v191, 1.0, v190
	v_add_f32_e32 v195, 1.0, v194
	v_add_f32_e32 v199, 1.0, v198
	v_fma_f32 v189, v186, v36, 1.0
	v_fma_f32 v193, v190, v36, 1.0
	v_fma_f32 v197, v194, v36, 1.0
	v_fma_f32 v201, v198, v36, 1.0
	v_rcp_f32_e32 v188, v187
	v_rcp_f32_e32 v192, v191
	v_rcp_f32_e32 v196, v195
	v_rcp_f32_e32 v200, v199
	v_log_f32_e32 v187, v187
	v_log_f32_e32 v191, v191
	v_log_f32_e32 v195, v195
	v_log_f32_e32 v199, v199
	v_log_f32_e32 v189, v189
	v_log_f32_e32 v193, v193
	v_log_f32_e32 v197, v197
	v_log_f32_e32 v201, v201
	v_mul_f32_e32 v188, v186, v188
	v_mul_f32_e32 v192, v190, v192
	v_mul_f32_e32 v196, v194, v196
	v_mul_f32_e32 v200, v198, v200
	v_mul_f32_e32 v187, 0xbf317218, v187
	v_mul_f32_e32 v191, 0xbf317218, v191
	v_mul_f32_e32 v195, 0xbf317218, v195
	v_mul_f32_e32 v199, 0xbf317218, v199
	v_mul_f32_e32 v148, v188, v204
	v_mul_f32_e32 v149, v192, v204
	v_mul_f32_e32 v150, v196, v204
	v_mul_f32_e32 v151, v200, v204
	v_min_f32_e32 v187, v48, v187
	v_min_f32_e32 v191, v47, v191
	v_min_f32_e32 v195, v46, v195
	v_min_f32_e32 v199, v45, v199
	v_fmac_f32_e32 v187, 0x3f317218, v189
	v_fmac_f32_e32 v191, 0x3f317218, v193
	v_fmac_f32_e32 v195, 0x3f317218, v197
	v_fmac_f32_e32 v199, 0x3f317218, v201
	v_add_f32_e32 v132, v187, v131
	v_add_f32_e32 v133, v191, v132
	v_add_f32_e32 v134, v195, v133
	v_add_f32_e32 v135, v199, v134
	v_lshlrev_b32_e32 v44, 16, v44
	v_lshlrev_b32_e32 v43, 16, v43
	v_lshlrev_b32_e32 v42, 16, v42
	v_lshlrev_b32_e32 v41, 16, v41
	v_max_f32_e64 v186, -v44, -v44
	v_max_f32_e64 v190, -v43, -v43
	v_max_f32_e64 v194, -v42, -v42
	v_max_f32_e64 v198, -v41, -v41
	v_min_f32_e32 v186, 0x42700000, v186
	v_min_f32_e32 v190, 0x42700000, v190
	v_min_f32_e32 v194, 0x42700000, v194
	v_min_f32_e32 v198, 0x42700000, v198
	v_mul_f32_e32 v186, 0x3fb8aa3b, v186
	v_mul_f32_e32 v190, 0x3fb8aa3b, v190
	v_mul_f32_e32 v194, 0x3fb8aa3b, v194
	v_mul_f32_e32 v198, 0x3fb8aa3b, v198
	v_exp_f32_e32 v186, v186
	v_exp_f32_e32 v190, v190
	v_exp_f32_e32 v194, v194
	v_exp_f32_e32 v198, v198
	v_add_f32_e32 v187, 1.0, v186
	v_add_f32_e32 v191, 1.0, v190
	v_add_f32_e32 v195, 1.0, v194
	v_add_f32_e32 v199, 1.0, v198
	v_fma_f32 v189, v186, v36, 1.0
	v_fma_f32 v193, v190, v36, 1.0
	v_fma_f32 v197, v194, v36, 1.0
	v_fma_f32 v201, v198, v36, 1.0
	v_rcp_f32_e32 v188, v187
	v_rcp_f32_e32 v192, v191
	v_rcp_f32_e32 v196, v195
	v_rcp_f32_e32 v200, v199
	v_log_f32_e32 v187, v187
	v_log_f32_e32 v191, v191
	v_log_f32_e32 v195, v195
	v_log_f32_e32 v199, v199
	v_log_f32_e32 v189, v189
	v_log_f32_e32 v193, v193
	v_log_f32_e32 v197, v197
	v_log_f32_e32 v201, v201
	v_mul_f32_e32 v188, v186, v188
	v_mul_f32_e32 v192, v190, v192
	v_mul_f32_e32 v196, v194, v196
	v_mul_f32_e32 v200, v198, v200
	v_mul_f32_e32 v187, 0xbf317218, v187
	v_mul_f32_e32 v191, 0xbf317218, v191
	v_mul_f32_e32 v195, 0xbf317218, v195
	v_mul_f32_e32 v199, 0xbf317218, v199
	v_mul_f32_e32 v152, v188, v204
	v_mul_f32_e32 v153, v192, v204
	v_mul_f32_e32 v154, v196, v204
	v_mul_f32_e32 v155, v200, v204
	v_min_f32_e32 v187, v44, v187
	v_min_f32_e32 v191, v43, v191
	v_min_f32_e32 v195, v42, v195
	v_min_f32_e32 v199, v41, v199
	v_fmac_f32_e32 v187, 0x3f317218, v189
	v_fmac_f32_e32 v191, 0x3f317218, v193
	v_fmac_f32_e32 v195, 0x3f317218, v197
	v_fmac_f32_e32 v199, 0x3f317218, v201
	v_add_f32_e32 v136, v187, v135
	v_add_f32_e32 v137, v191, v136
	v_add_f32_e32 v138, v195, v137
	v_add_f32_e32 v139, v199, v138
	v_lshlrev_b32_e32 v39, 16, v39
	v_lshlrev_b32_e32 v38, 16, v38
	v_lshlrev_b32_e32 v37, 16, v37
	v_lshlrev_b32_e32 v35, 16, v35
	v_max_f32_e64 v186, -v39, -v39
	v_max_f32_e64 v190, -v38, -v38
	v_max_f32_e64 v194, -v37, -v37
	v_max_f32_e64 v198, -v35, -v35
	v_min_f32_e32 v186, 0x42700000, v186
	v_min_f32_e32 v190, 0x42700000, v190
	v_min_f32_e32 v194, 0x42700000, v194
	v_min_f32_e32 v198, 0x42700000, v198
	v_mul_f32_e32 v186, 0x3fb8aa3b, v186
	v_mul_f32_e32 v190, 0x3fb8aa3b, v190
	v_mul_f32_e32 v194, 0x3fb8aa3b, v194
	v_mul_f32_e32 v198, 0x3fb8aa3b, v198
	v_exp_f32_e32 v186, v186
	v_exp_f32_e32 v190, v190
	v_exp_f32_e32 v194, v194
	v_exp_f32_e32 v198, v198
	v_add_f32_e32 v187, 1.0, v186
	v_add_f32_e32 v191, 1.0, v190
	v_add_f32_e32 v195, 1.0, v194
	v_add_f32_e32 v199, 1.0, v198
	v_fma_f32 v189, v186, v36, 1.0
	v_fma_f32 v193, v190, v36, 1.0
	v_fma_f32 v197, v194, v36, 1.0
	v_fma_f32 v201, v198, v36, 1.0
	v_rcp_f32_e32 v188, v187
	v_rcp_f32_e32 v192, v191
	v_rcp_f32_e32 v196, v195
	v_rcp_f32_e32 v200, v199
	v_log_f32_e32 v187, v187
	v_log_f32_e32 v191, v191
	v_log_f32_e32 v195, v195
	v_log_f32_e32 v199, v199
	v_log_f32_e32 v189, v189
	v_log_f32_e32 v193, v193
	v_log_f32_e32 v197, v197
	v_log_f32_e32 v201, v201
	v_mul_f32_e32 v188, v186, v188
	v_mul_f32_e32 v192, v190, v192
	v_mul_f32_e32 v196, v194, v196
	v_mul_f32_e32 v200, v198, v200
	v_mul_f32_e32 v187, 0xbf317218, v187
	v_mul_f32_e32 v191, 0xbf317218, v191
	v_mul_f32_e32 v195, 0xbf317218, v195
	v_mul_f32_e32 v199, 0xbf317218, v199
	v_mul_f32_e32 v156, v188, v204
	v_mul_f32_e32 v157, v192, v204
	v_mul_f32_e32 v158, v196, v204
	v_mul_f32_e32 v159, v200, v204
	v_min_f32_e32 v187, v39, v187
	v_min_f32_e32 v191, v38, v191
	v_min_f32_e32 v195, v37, v195
	v_min_f32_e32 v199, v35, v199
	v_fmac_f32_e32 v187, 0x3f317218, v189
	v_fmac_f32_e32 v191, 0x3f317218, v193
	v_fmac_f32_e32 v195, 0x3f317218, v197
	v_fmac_f32_e32 v199, 0x3f317218, v201
	v_add_f32_e32 v140, v187, v139
	v_add_f32_e32 v141, v191, v140
	v_add_f32_e32 v142, v195, v141
	v_add_f32_e32 v143, v199, v142
	s_mov_b32 s3, 0xbfb8aa3b
	v_lshrrev_b32_e32 v28, 8, v28
	s_movk_i32 s2, 0x410
	v_mul_i32_i24_e32 v28, 0xd800, v28
	v_mad_u32_u24 v40, v29, s2, v21
	v_lshl_add_u32 v40, v40, 2, v28
	v_mov_b32_e32 v160, v40
	v_add_u32_e32 v52, 0x4400, v40
	v_and_b32_e32 v33, 0xff, v33
	v_mul_u32_u24_e32 v31, 0x48, v31
	v_add_u32_e32 v51, 0x400, v40
	v_add_u32_e32 v49, 0x4800, v40
	v_lshlrev_b32_e32 v31, 1, v31
	v_lshlrev_b32_e32 v30, 1, v30
	v_cmp_lt_u32_e32 vcc, 63, v33
	s_nop 0
	v_add_u32_e32 v47, 0x800, v40
	v_add_u32_e32 v45, 0x4c00, v40
	s_nop 0
	s_nop 0
	v_add_u32_e32 v43, 0xc00, v40
	v_add_u32_e32 v40, 0x5000, v40
	v_lshl_add_u32 v34, v33, 2, v28
	v_add_u32_e32 v161, 0x400, v160
	v_add_u32_e32 v162, 0x800, v160
	v_add_u32_e32 v163, 0xc00, v160
	v_add_u32_e32 v164, 0x4400, v160
	v_add_u32_e32 v165, 0x4800, v160
	v_add_u32_e32 v166, 0x4c00, v160
	v_add_u32_e32 v167, 0x5000, v160
	ds_write2_b32 v160, v128, v129 offset1:65
	ds_write2_b32 v164, v144, v145 offset1:65
	ds_write2_b32 v160, v130, v131 offset0:130 offset1:195
	ds_write2_b32 v164, v146, v147 offset0:130 offset1:195
	ds_write2_b32 v161, v132, v133 offset0:4 offset1:69
	ds_write2_b32 v165, v148, v149 offset0:4 offset1:69
	ds_write2_b32 v161, v134, v135 offset0:134 offset1:199
	ds_write2_b32 v165, v150, v151 offset0:134 offset1:199
	ds_write2_b32 v162, v136, v137 offset0:8 offset1:73
	ds_write2_b32 v166, v152, v153 offset0:8 offset1:73
	ds_write2_b32 v162, v138, v139 offset0:138 offset1:203
	ds_write2_b32 v166, v154, v155 offset0:138 offset1:203
	ds_write2_b32 v167, v156, v157 offset0:12 offset1:77
	ds_write2_b32 v163, v140, v141 offset0:12 offset1:77
	ds_write2_b32 v163, v142, v143 offset0:142 offset1:207
	ds_write2_b32 v167, v158, v159 offset0:142 offset1:207
	ds_write_b32 v34, v143 offset:53248
	v_add3_u32 v34, v28, v31, v30
	v_add3_u32 v30, v28, v30, v31
	ds_write_b16 v34, v12 offset:34816
	ds_write_b16_d16_hi v30, v12 offset:34960
	ds_write_b16 v34, v13 offset:35104
	ds_write_b16_d16_hi v30, v13 offset:35248
	ds_write_b16 v34, v14 offset:35392
	ds_write_b16_d16_hi v30, v14 offset:35536
	ds_write_b16 v34, v15 offset:35680
	ds_write_b16_d16_hi v30, v15 offset:35824
	ds_write_b16 v34, v8 offset:35968
	ds_write_b16_d16_hi v30, v8 offset:36112
	ds_write_b16 v34, v9 offset:36256
	ds_write_b16_d16_hi v30, v9 offset:36400
	ds_write_b16 v34, v10 offset:36544
	ds_write_b16_d16_hi v30, v10 offset:36688
	ds_write_b16 v34, v11 offset:36832
	ds_write_b16_d16_hi v30, v11 offset:36976
	s_waitcnt lgkmcnt(0)
	s_barrier
	s_and_saveexec_b64 s[2:3], vcc
	s_cbranch_execz .LBB0_238
	v_lshlrev_b32_e32 v8, 2, v21
	s_mov_b32 s4, 0xd000
	v_add3_u32 v8, v28, v8, s4
	v_mov_b32_e32 v20, 0
	s_mov_b64 s[4:5], 0
